# v9 + P3: WGs 0..31 (two sample-attention units each) take 8 instead of 4 dilated-attention groups; others start at group 256
# speedup vs baseline: 1.0002x; 1.0002x over previous
; __global__ void __launch_bounds__(512, 2) mega_fwd(Args args) {
;     ...
;             const bool bal = (G == 256);
;             const int vj = (bx & 7) * 28 + ((bx >> 3) - 4);
;             int gid = bal ? (bx < 32 ? bx * 4 : 128 + vj) : bx;
;             const int gstep = bal ? (bx < 32 ? 1 : 224) : G, gend = bal && bx < 32 ? bx * 4 + 4 : NGRP;
;             bf16x8 qf[8];
;     ...
;             if (gid < gend) { DG_LOAD(gid); DG_QLOAD(gid); }
.LBB0_402:
	s_cmpk_eq_i32 s3, 0x100
	s_cselect_b64 s[4:5], -1, 0
	s_and_b64 vcc, exec, s[4:5]
	s_mov_b32 s53, s2
	s_waitcnt lgkmcnt(0)
	s_barrier
	s_cbranch_vccz .LBB0_407
	s_cmp_gt_i32 s2, 31
	s_cbranch_scc0 .LBB0_405
	s_and_b32 s6, s2, 7
	s_mul_i32 s6, s6, 28
	s_ashr_i32 s7, s2, 3
	s_add_i32 s6, s7, s6
	s_add_i32 s53, s6, 0xfc
	s_cbranch_execz .LBB0_406
	s_branch .LBB0_407
.LBB0_405:
.LBB0_406:
	s_mul_i32 s53, s2, 8
.LBB0_407:
	s_cmp_lt_i32 s2, 32
	s_cselect_b64 s[6:7], -1, 0
	s_mul_i32 s10, s2, 8
	s_and_b64 s[8:9], s[6:7], s[4:5]
	s_add_i32 s10, s10, 8
	s_and_b64 s[8:9], s[8:9], exec
	s_cselect_b32 s27, s10, 0xc00
	s_cmp_lt_i32 s53, s27
	s_cselect_b64 s[8:9], -1, 0
	s_cmp_ge_i32 s53, s27
	s_cbranch_scc1 .LBB0_417
	s_and_b32 s10, s53, 0x380
	s_and_b32 s11, s53, 0x7f
	s_and_b32 s12, s53, 0xfffffc00
	s_cmpk_eq_i32 s12, 0x400
	s_cselect_b32 s12, 2, 4
	s_cmpk_gt_u32 s53, 0x3ff
	s_cselect_b32 s14, s12, 0
	s_lshr_b32 s12, 0x80, s14
	s_xor_b32 s13, s14, 7
	s_add_i32 s12, s12, -1
	s_lshr_b32 s15, s11, s13
	s_and_b32 s11, s12, s11
	s_lshl_b32 s20, s11, 7
	v_lshrrev_b32_e32 v0, 4, v193
	v_or_b32_e32 v0, s20, v0
	v_add_u32_e32 v6, 0xffffff80, v0
	s_lshl_b32 s10, s10, 1
	v_lshlrev_b32_e32 v0, 3, v193
	s_add_u32 s12, s18, s10
	v_and_b32_e32 v0, 0x78, v0
	v_mov_b32_e32 v3, 0
	s_addc_u32 s13, s19, 0
	v_lshlrev_b32_e32 v2, 1, v0
	v_lshlrev_b32_e32 v4, s14, v6
	v_mov_b32_e32 v98, v3
	v_mov_b32_e32 v99, v3
	v_lshl_add_u64 v[0:1], s[12:13], 0, v[2:3]
	s_mov_b64 s[12:13], 0x20000000
	v_add_u32_e32 v4, s15, v4
	v_mov_b32_e32 v96, v3
	v_mov_b32_e32 v97, v3
	v_mov_b64_e32 v[102:103], v[98:99]
	v_mov_b64_e32 v[106:107], v[98:99]
	v_lshl_add_u64 v[0:1], v[0:1], 0, s[12:13]
	v_cmp_lt_i32_e32 vcc, -1, v4
	s_mov_b32 s11, 0
	v_mov_b64_e32 v[100:101], v[96:97]
	v_mov_b64_e32 v[104:105], v[96:97]
	s_and_saveexec_b64 s[12:13], vcc
	s_cbranch_execz .LBB0_410
	v_mov_b32_e32 v5, v3
	v_lshlrev_b64 v[8:9], 11, v[4:5]
	v_lshlrev_b64 v[4:5], 13, v[4:5]
	v_lshl_add_u64 v[4:5], s[18:19], 0, v[4:5]
	v_lshl_add_u64 v[4:5], v[4:5], 0, s[10:11]
	v_lshl_add_u64 v[4:5], v[4:5], 0, v[2:3]
	v_lshl_add_u64 v[8:9], v[0:1], 0, v[8:9]
	v_add_co_u32_e32 v4, vcc, 0x15d01000, v4
	s_nop 1
	v_addc_co_u32_e32 v5, vcc, 0, v5, vcc
	global_load_dwordx4 v[100:103], v[8:9], off
	global_load_dwordx4 v[104:107], v[4:5], off offset:2048
